# attention sub-step 1: all 16 exps and 8 converts ahead of the per-tile barrier, the full eight-MFMA P.V run behind the release
# baseline (speedup 1.0000x reference)
; __device__ __forceinline__ unsigned pk2(float lo, float hi) { return pg8::cvt_pk_bf16(lo, hi); }
; #define MFMA32(a, b, c) __builtin_amdgcn_mfma_f32_32x32x16_bf16((a), (b), (c), 0, 0, 0)
; __device__ __forceinline__ void attn_phase(const Args& a, int l, bool with_ctx, unsigned char* lds) {
;     ...
;                 for (int r = 0; r < 16; ++r) { S[r] = __builtin_amdgcn_exp2f(S[r]); ps += S[r]; }
;                 lrun += ps;
;                 u32x4 p0, p1;
;                 p0.x = pk2(S[0], S[1]); p0.y = pk2(S[2], S[3]); p0.z = pk2(S[4], S[5]); p0.w = pk2(S[6], S[7]);
;                 p1.x = pk2(S[8], S[9]); p1.y = pk2(S[10], S[11]); p1.z = pk2(S[12], S[13]); p1.w = pk2(S[14], S[15]);
;                 const bf16x8 pa0 = __builtin_bit_cast(bf16x8, p0), pa1 = __builtin_bit_cast(bf16x8, p1);
; #pragma unroll
;                 for (int j = 0; j < 4; ++j) O[j] = MFMA32(vf[2 * j], pa0, O[j]);
; #pragma unroll
;                 for (int j = 0; j < 4; ++j) O[j] = MFMA32(vf[2 * j + 1], pa1, O[j]);
;             }
;             if (t + 1 < nt) { unsigned char* kd = kdst + (cur ^ 1) * BUF; unsigned char* vd = vdst + (cur ^ 1) * BUF;
;                 *(u32x4*)kd = k0; *(u32x4*)(kd + 9216) = k1; *(u32x4*)vd = v0; *(u32x4*)(vd + 9216) = v1; }
;             __syncthreads();
.LBB0_412:
	v_exp_f32_e32 v67, v68
	v_exp_f32_e32 v68, v69
	v_exp_f32_e32 v69, v70
	v_exp_f32_e32 v70, v71
	v_exp_f32_e32 v71, v72
	v_exp_f32_e32 v72, v73
	v_exp_f32_e32 v73, v74
	v_exp_f32_e32 v74, v75
	v_cvt_pk_bf16_f32 v184, v67, v68
	v_cvt_pk_bf16_f32 v185, v69, v70
	v_cvt_pk_bf16_f32 v186, v71, v72
	v_cvt_pk_bf16_f32 v187, v73, v74
	v_exp_f32_e32 v75, v76
	v_exp_f32_e32 v76, v77
	v_exp_f32_e32 v77, v78
	v_exp_f32_e32 v78, v79
	v_exp_f32_e32 v79, v80
	v_exp_f32_e32 v80, v81
	v_exp_f32_e32 v81, v82
	v_exp_f32_e32 v82, v83
	v_cvt_pk_bf16_f32 v214, v75, v76
	v_cvt_pk_bf16_f32 v215, v77, v78
	v_cvt_pk_bf16_f32 v216, v79, v80
	v_cvt_pk_bf16_f32 v217, v81, v82
	s_andn2_b64 vcc, exec, s[10:11]
	s_waitcnt lgkmcnt(0)
	s_barrier
	v_mfma_f32_32x32x16_bf16 v[50:65], v[136:139], v[184:187], v[50:65]
	v_mfma_f32_32x32x16_bf16 v[34:49], v[140:143], v[184:187], v[34:49]
	s_waitcnt lgkmcnt(7)
	v_mfma_f32_32x32x16_bf16 v[18:33], v[144:147], v[184:187], v[18:33]
	s_waitcnt lgkmcnt(5)
	v_mfma_f32_32x32x16_bf16 v[2:17], v[132:135], v[184:187], v[2:17]
	v_mfma_f32_32x32x16_bf16 v[50:65], v[116:119], v[214:217], v[50:65]
	v_mfma_f32_32x32x16_bf16 v[34:49], v[120:123], v[214:217], v[34:49]
	v_mfma_f32_32x32x16_bf16 v[18:33], v[124:127], v[214:217], v[18:33]
	s_waitcnt lgkmcnt(4)
	v_mfma_f32_32x32x16_bf16 v[2:17], v[128:131], v[214:217], v[2:17]
